# RWKV solve LDS-operand prefetch + A1 rows/conv weights preloaded per item (no item remap)
# baseline (speedup 1.0000x reference)
; __device__ __forceinline__ float bflo(unsigned u) { return __uint_as_float(u << 16); }
; __device__ __forceinline__ float bfhi(unsigned u) { return __uint_as_float(u & 0xFFFF0000u); }
; __device__ __forceinline__ float siluf_(float x) { return x * frcp(1.0f + __expf(-x)); }
; __device__ __forceinline__ void phase_a1(const P& p, const Ctx& c, int seg) {
;     ...
;             u32x2 nraw = *(const u32x2*)(P0 + (unsigned)(row0 * ML_W + n * 4));
; #pragma unroll 1
;             for (int tt = 0; tt < 8; ++tt) {
;                 const unsigned row = (unsigned)(row0 + tt);
;                 const u32x2 raw = nraw;
;                 if (tt + 1 < 8) nraw = *(const u32x2*)(P0 + (unsigned)((row + 1) * ML_W + n * 4));
;                 float u[4] = {bflo(raw.x), bfhi(raw.x), bflo(raw.y), bfhi(raw.y)}, xc[4], q[4], k[4], v[4];
;                 { int nn = n; asm volatile("" : "+v"(nn));
;                   const f32x4 cb = *(const f32x4*)(p.ml_conv_b + nn * 4), c0 = *(const f32x4*)(p.ml_conv_w + nn * 4), c1 = *(const f32x4*)(p.ml_conv_w + DMIX + nn * 4),
;                               c2 = *(const f32x4*)(p.ml_conv_w + 2 * DMIX + nn * 4), c3 = *(const f32x4*)(p.ml_conv_w + 3 * DMIX + nn * 4);
; #pragma unroll
;                   for (int i = 0; i < 4; ++i) { const float y = cb[i] + c0[i] * um[0][i] + c1[i] * um[1][i] + c2[i] * um[2][i] + c3[i] * u[i]; xc[i] = siluf_(y); } }
;                 const float ks = 0.05103103630798288f;
; #pragma unroll
;                 for (int o = 0; o < 4; ++o) { q[o] = xc[0] * wq[0][o] + xc[1] * wq[1][o] + xc[2] * wq[2][o] + xc[3] * wq[3][o];
;                     k[o] = (xc[0] * wk[0][o] + xc[1] * wk[1][o] + xc[2] * wk[2][o] + xc[3] * wk[3][o]) * ks;
;                     v[o] = u[0] * wv[0][o] + u[1] * wv[1][o] + u[2] * wv[2][o] + u[3] * wv[3][o]; }
; #pragma unroll
;                 for (int g = 0; g < 8; ++g) red[(tt * 8 + g) * 384 + n] = xc[0] * G12[0][g] + xc[1] * G12[1][g] + xc[2] * G12[2][g] + xc[3] * G12[3][g] + u[0] * G3[0][g] + u[1] * G3[1][g] + u[2] * G3[2][g] + u[3] * G3[3][g];
.LBB0_271:
	v_lshl_add_u32 v4, s46, 15, v2
	s_waitcnt lgkmcnt(0)
	v_lshl_add_u64 v[98:99], v[4:5], 1, s[10:11]
	global_load_dwordx2 v[116:117], v[98:99], off
	v_lshlrev_b32_e32 v208, 2, v170
	v_ashrrev_i32_e32 v209, 31, v208
	v_lshlrev_b64 v[208:209], 2, v[208:209]
	v_lshl_add_u64 v[210:211], s[22:23], 0, v[208:209]
	global_load_dwordx4 v[218:221], v[210:211], off
	v_lshl_add_u64 v[210:211], s[20:21], 0, v[208:209]
	global_load_dwordx4 v[222:225], v[210:211], off
	v_lshl_add_u64 v[210:211], s[54:55], 0, v[208:209]
	global_load_dwordx4 v[226:229], v[210:211], off
	v_lshl_add_u64 v[210:211], s[56:57], 0, v[208:209]
	global_load_dwordx4 v[230:233], v[210:211], off
	v_lshl_add_u64 v[210:211], s[68:69], 0, v[208:209]
	global_load_dwordx4 v[234:237], v[210:211], off
	s_mov_b64 s[98:99], 0x2000
	v_lshl_add_u64 v[210:211], v[98:99], 0, s[98:99]
	global_load_dwordx2 v[238:239], v[210:211], off
	v_lshl_add_u64 v[210:211], v[210:211], 0, s[98:99]
	global_load_dwordx2 v[240:241], v[210:211], off
	v_lshl_add_u64 v[210:211], v[210:211], 0, s[98:99]
	global_load_dwordx2 v[242:243], v[210:211], off
	v_lshl_add_u64 v[210:211], v[210:211], 0, s[98:99]
	global_load_dwordx2 v[244:245], v[210:211], off
	v_lshl_add_u64 v[210:211], v[210:211], 0, s[98:99]
	global_load_dwordx2 v[246:247], v[210:211], off
	v_lshl_add_u64 v[210:211], v[210:211], 0, s[98:99]
	global_load_dwordx2 v[248:249], v[210:211], off
	v_lshl_add_u64 v[210:211], v[210:211], 0, s[98:99]
	global_load_dwordx2 v[250:251], v[210:211], off
	s_waitcnt vmcnt(13)
	v_lshlrev_b32_e32 v100, 16, v102
	v_and_b32_e32 v101, 0xffff0000, v102
	v_lshlrev_b32_e32 v99, 16, v103
	v_and_b32_e32 v137, 0xffff0000, v103
	v_lshlrev_b32_e32 v102, 16, v104
	v_and_b32_e32 v103, 0xffff0000, v104
	v_lshlrev_b32_e32 v104, 16, v105
	v_and_b32_e32 v138, 0xffff0000, v105
	v_lshlrev_b32_e32 v118, 16, v106
	v_and_b32_e32 v119, 0xffff0000, v106
	v_lshlrev_b32_e32 v98, 16, v107
	v_and_b32_e32 v120, 0xffff0000, v107
	s_mov_b32 s8, -16
	v_mov_b32_e32 v4, v136
	v_mov_b32_e32 v106, v135
	v_mov_b32_e32 v139, v3
	s_waitcnt vmcnt(0)
	v_mov_b64_e32 v[108:109], v[116:117]
	s_branch .LBB0_273
.LBB0_272:
	v_lshlrev_b32_e32 v113, 16, v117
	v_and_b32_e32 v110, 0xffff0000, v117
	v_lshlrev_b32_e32 v114, 16, v116
	v_and_b32_e32 v115, 0xffff0000, v116
	v_pk_fma_f32 v[116:117], v[118:119], v[222:223], v[218:219]
	v_mul_f32_e32 v121, v120, v225
	v_pk_fma_f32 v[116:117], v[100:101], v[226:227], v[116:117]
	v_mul_f32_e32 v127, v137, v229
	v_pk_fma_f32 v[116:117], v[102:103], v[230:231], v[116:117]
	v_mov_b32_e32 v112, v232
	v_pk_fma_f32 v[116:117], v[234:235], v[114:115], v[116:117]
	v_mul_f32_e32 v129, v138, v233
	v_mul_f32_e32 v105, 0xbfb8aa3b, v116
	v_exp_f32_e32 v105, v105
	v_mul_f32_e32 v131, v237, v110
	v_add_f32_e32 v105, 1.0, v105
	v_rcp_f32_e32 v118, v105
	v_mul_f32_e32 v105, 0xbfb8aa3b, v117
	v_exp_f32_e32 v105, v105
	s_nop 0
	v_add_f32_e32 v105, 1.0, v105
	v_rcp_f32_e32 v119, v105
	v_mov_b32_e32 v105, v236
	v_pk_mul_f32 v[122:123], v[104:105], v[112:113]
	v_pk_mul_f32 v[116:117], v[116:117], v[118:119]
	v_mov_b32_e32 v118, v224
	v_mov_b32_e32 v119, v228
	v_pk_mul_f32 v[118:119], v[98:99], v[118:119]
	v_mov_b32_e32 v128, v122
	v_mov_b32_e32 v120, v118
	v_pk_add_f32 v[120:121], v[220:221], v[120:121]
	v_mov_b32_e32 v126, v119
	v_pk_add_f32 v[118:119], v[120:121], v[126:127]
	v_mov_b32_e32 v130, v123
	v_pk_add_f32 v[118:119], v[128:129], v[118:119]
	v_pk_mul_f32 v[124:125], v[14:15], v[114:115]
	v_pk_add_f32 v[118:119], v[118:119], v[130:131]
	v_pk_mul_f32 v[130:131], v[16:17], v[114:115]
	v_mul_f32_e32 v98, 0xbfb8aa3b, v118
	v_exp_f32_e32 v98, v98
	v_pk_fma_f32 v[124:125], v[44:45], v[114:115], v[124:125] op_sel:[0,1,0] op_sel_hi:[1,0,1]
	v_pk_fma_f32 v[130:131], v[46:47], v[114:115], v[130:131] op_sel:[0,1,0] op_sel_hi:[1,0,1]
	v_mul_f32_e32 v105, v84, v116
	v_add_f32_e32 v98, 1.0, v98
	v_rcp_f32_e32 v120, v98
	v_mul_f32_e32 v98, 0xbfb8aa3b, v119
	v_exp_f32_e32 v98, v98
	v_fmac_f32_e32 v105, v163, v117
	v_pk_mul_f32 v[126:127], v[8:9], v[116:117]
	v_add_f32_e32 v98, 1.0, v98
	v_rcp_f32_e32 v121, v98
	v_mov_b32_e32 v98, v113
	v_pk_fma_f32 v[124:125], v[38:39], v[98:99], v[124:125] op_sel_hi:[1,0,1]
	v_pk_fma_f32 v[130:131], v[40:41], v[98:99], v[130:131] op_sel_hi:[1,0,1]
	v_mul_f32_e32 v98, v152, v116
	v_pk_mul_f32 v[120:121], v[118:119], v[120:121]
	v_fmac_f32_e32 v98, v162, v117
	v_fmac_f32_e32 v98, v184, v120
	v_fmac_f32_e32 v105, v76, v120
	v_fmac_f32_e32 v98, v62, v121
	v_fmac_f32_e32 v105, v63, v121
	v_fmac_f32_e32 v98, v154, v114
	v_fmac_f32_e32 v105, v92, v114
	v_fmac_f32_e32 v98, v182, v115
	v_fmac_f32_e32 v105, v183, v115
	v_fmac_f32_e32 v98, v196, v113
	v_fmac_f32_e32 v105, v197, v113
	v_fmac_f32_e32 v98, v66, v110
	v_fmac_f32_e32 v105, v67, v110
	ds_write2st64_b32 v139, v98, v105 offset1:6
	v_mul_f32_e32 v98, v156, v116
	v_mul_f32_e32 v105, v82, v116
	v_fmac_f32_e32 v98, v176, v117
	v_fmac_f32_e32 v105, v177, v117
	v_fmac_f32_e32 v98, v192, v120
	v_fmac_f32_e32 v105, v74, v120
	v_fmac_f32_e32 v98, v58, v121
	v_fmac_f32_e32 v105, v59, v121
	v_fmac_f32_e32 v98, v166, v114
	v_fmac_f32_e32 v105, v90, v114
	v_fmac_f32_e32 v98, v190, v115
	v_fmac_f32_e32 v105, v191, v115
	v_fmac_f32_e32 v98, v200, v113
	v_fmac_f32_e32 v105, v201, v113
	v_fmac_f32_e32 v98, v64, v110
	v_fmac_f32_e32 v105, v65, v110
	ds_write2st64_b32 v139, v98, v105 offset0:12 offset1:18
	v_mul_f32_e32 v98, v150, v116
	v_mul_f32_e32 v105, v80, v116
	v_fmac_f32_e32 v98, v164, v117
	v_fmac_f32_e32 v105, v165, v117
	v_fmac_f32_e32 v98, v186, v120
	v_fmac_f32_e32 v105, v72, v120
	v_fmac_f32_e32 v98, v54, v121
	v_fmac_f32_e32 v105, v55, v121
	v_fmac_f32_e32 v98, v158, v114
; #define LAS __attribute__((address_space(3)))
; __device__ __forceinline__ bf16_t f2bf(float f) { const __bf16 r = (__bf16)f; bf16_t u; __builtin_memcpy(&u, &r, 2); return u; }
; __device__ __forceinline__ unsigned pk2(float lo, float hi) { const bf2_t r = __builtin_convertvector((f32x2){lo, hi}, bf2_t); unsigned u; __builtin_memcpy(&u, &r, 4); return u; }
; __device__ __forceinline__ void phase_a1(const P& p, const Ctx& c, int seg) {
;     ...
;                 for (int g = 0; g < 8; ++g) red[(tt * 8 + g) * 384 + n] = xc[0] * G12[0][g] + xc[1] * G12[1][g] + xc[2] * G12[2][g] + xc[3] * G12[3][g] + u[0] * G3[0][g] + u[1] * G3[1][g] + u[2] * G3[2][g] + u[3] * G3[3][g];
;                 u32x2 w; w.x = pk2(q[0], q[1]); w.y = pk2(q[2], q[3]); *(u32x2*)(Qb + (unsigned)(row * DMIX + n * 4)) = w;
;                 w.x = pk2(k[0], k[1]); w.y = pk2(k[2], k[3]); *(u32x2*)(Kb + (unsigned)(row * DMIX + n * 4)) = w;
;                 w.x = pk2(xc[0], xc[1]); w.y = pk2(xc[2], xc[3]); *(u32x2*)(XC + (unsigned)(row * DMIX + n * 4)) = w;
;                 w.x = pk2(v[0], v[1]); w.y = pk2(v[2], v[3]); *(u32x2*)(VF + (unsigned)(row * DMIX + n * 4)) = w;
; #pragma unroll
;                 for (int o = 0; o < 4; ++o) { kst[(o * 384 + n) * 8 + tt] = f2bf(k[o]); vst[(o * 384 + n) * 8 + tt] = f2bf(v[o]); }
; #pragma unroll
;                 for (int i = 0; i < 4; ++i) { um[0][i] = um[1][i]; um[1][i] = um[2][i]; um[2][i] = u[i]; }
;             }
;             const int hd = n / 96, dch = (n % 96) * 4;
; #pragma unroll
;             for (int o = 0; o < 4; ++o) { const unsigned off = (unsigned)(((b * 4 + hd) * 384 + dch + o) * SEGT + tl0);
;                 *(u32x4*)(KT + off) = *(const LAS u32x4*)(kst + (o * 384 + n) * 8); *(u32x4*)(VT + off) = *(const LAS u32x4*)(vst + (o * 384 + n) * 8); }
	v_fmac_f32_e32 v105, v88, v114
	v_fmac_f32_e32 v98, v180, v115
	v_fmac_f32_e32 v105, v181, v115
	v_fmac_f32_e32 v98, v198, v113
	v_fmac_f32_e32 v105, v199, v113
	v_fmac_f32_e32 v98, v70, v110
	v_fmac_f32_e32 v105, v71, v110
	ds_write2st64_b32 v139, v98, v105 offset0:24 offset1:30
	v_mul_f32_e32 v98, v160, v116
	v_mul_f32_e32 v105, v78, v116
	v_pk_mul_f32 v[118:119], v[6:7], v[116:117]
	v_fmac_f32_e32 v98, v178, v117
	v_fmac_f32_e32 v105, v179, v117
	v_pk_fma_f32 v[118:119], v[52:53], v[116:117], v[118:119] op_sel:[0,1,0] op_sel_hi:[1,0,1]
	v_fmac_f32_e32 v98, v194, v120
	v_fmac_f32_e32 v105, v42, v120
	v_pk_fma_f32 v[118:119], v[22:23], v[120:121], v[118:119] op_sel_hi:[1,0,1]
	v_fmac_f32_e32 v98, v56, v121
	v_fmac_f32_e32 v105, v57, v121
	v_pk_fma_f32 v[122:123], v[18:19], v[120:121], v[118:119] op_sel:[0,1,0]
	v_pk_mul_f32 v[118:119], v[10:11], v[116:117]
	v_fmac_f32_e32 v98, v168, v114
	v_fmac_f32_e32 v105, v86, v114
	v_pk_fma_f32 v[118:119], v[48:49], v[116:117], v[118:119] op_sel:[0,1,0] op_sel_hi:[1,0,1]
	v_fmac_f32_e32 v98, v188, v115
	v_fmac_f32_e32 v105, v189, v115
	v_pk_fma_f32 v[118:119], v[30:31], v[120:121], v[118:119] op_sel_hi:[1,0,1]
	v_pk_fma_f32 v[126:127], v[60:61], v[116:117], v[126:127] op_sel:[0,1,0] op_sel_hi:[1,0,1]
	v_fmac_f32_e32 v98, v202, v113
	v_fmac_f32_e32 v105, v203, v113
	v_pk_fma_f32 v[118:119], v[26:27], v[120:121], v[118:119] op_sel:[0,1,0]
	v_pk_fma_f32 v[126:127], v[24:25], v[120:121], v[126:127] op_sel_hi:[1,0,1]
	v_fmac_f32_e32 v98, v68, v110
	v_fmac_f32_e32 v105, v69, v110
	v_pk_mul_f32 v[118:119], v[118:119], s[48:49] op_sel_hi:[1,0]
	v_pk_fma_f32 v[128:129], v[20:21], v[120:121], v[126:127] op_sel:[0,1,0]
	v_pk_mul_f32 v[126:127], v[12:13], v[116:117]
	ds_write2st64_b32 v139, v98, v105 offset0:36 offset1:42
	v_add_u32_e32 v105, s8, v134
	v_pk_fma_f32 v[124:125], v[34:35], v[110:111], v[124:125] op_sel_hi:[1,0,1]
	v_pk_fma_f32 v[126:127], v[50:51], v[116:117], v[126:127] op_sel:[0,1,0] op_sel_hi:[1,0,1]
	v_cvt_pk_bf16_f32 v98, v118, s0
	v_add_u32_e32 v107, 0x18010, v105
	v_pk_fma_f32 v[126:127], v[32:33], v[120:121], v[126:127] op_sel_hi:[1,0,1]
	ds_write_b16 v107, v98
	v_cvt_pk_bf16_f32 v98, v124, s0
	v_add_u32_e32 v107, 0x1e010, v105
	v_pk_fma_f32 v[126:127], v[28:29], v[120:121], v[126:127] op_sel:[0,1,0]
	ds_write_b16 v107, v98
	v_cvt_pk_bf16_f32 v98, v119, s0
	v_add_u32_e32 v107, 0x19810, v105
	v_pk_mul_f32 v[126:127], v[126:127], s[48:49] op_sel_hi:[1,0]
	ds_write_b16 v107, v98
	v_cvt_pk_bf16_f32 v98, v125, s0
	v_add_u32_e32 v107, 0x1f810, v105
	v_pk_fma_f32 v[130:131], v[36:37], v[110:111], v[130:131] op_sel_hi:[1,0,1]
	ds_write_b16 v107, v98
	v_cvt_pk_bf16_f32 v98, v126, s0
	v_add_u32_e32 v107, 0x1b010, v105
	v_cvt_pk_bf16_f32 v122, v122, v123
	v_cvt_pk_bf16_f32 v123, v128, v129
	v_lshlrev_b64 v[128:129], 1, v[4:5]
	ds_write_b16 v107, v98
	v_cvt_pk_bf16_f32 v98, v130, s0
	v_add_u32_e32 v107, 0x21010, v105
	v_cvt_pk_bf16_f32 v116, v116, v117
	v_cvt_pk_bf16_f32 v117, v120, v121
	v_lshl_add_u64 v[120:121], s[26:27], 0, v[128:129]
	ds_write_b16 v107, v98
	v_cvt_pk_bf16_f32 v98, v127, s0
	v_add_u32_e32 v107, 0x1c810, v105
	v_lshl_add_u64 v[140:141], s[12:13], 0, v[128:129]
	global_store_dwordx2 v[120:121], v[116:117], off
	v_cvt_pk_bf16_f32 v116, v124, v125
	v_cvt_pk_bf16_f32 v117, v130, v131
	v_lshl_add_u64 v[120:121], s[30:31], 0, v[128:129]
	ds_write_b16 v107, v98
	v_cvt_pk_bf16_f32 v98, v131, s0
	v_add_u32_e32 v105, 0x22810, v105
	s_add_i32 s8, s8, 2
	global_store_dwordx2 v[140:141], v[122:123], off
	v_cvt_pk_bf16_f32 v122, v118, v119
	v_cvt_pk_bf16_f32 v123, v126, v127
	v_lshl_add_u64 v[140:141], s[14:15], 0, v[128:129]
	global_store_dwordx2 v[120:121], v[116:117], off
	ds_write_b16 v105, v98
	v_add_u32_e32 v139, 0x3000, v139
	v_add_u32_e32 v4, 0x600, v4
	s_cmp_eq_u32 s8, 0
	v_mov_b32_e32 v118, v100
	v_mov_b32_e32 v119, v101
	v_mov_b32_e32 v98, v99
	v_mov_b32_e32 v120, v137
	v_mov_b32_e32 v100, v102
	v_mov_b32_e32 v101, v103
	v_mov_b32_e32 v99, v104
	v_mov_b32_e32 v137, v138
	v_mov_b32_e32 v102, v114
	v_mov_b32_e32 v103, v115
	v_mov_b32_e32 v104, v113
	v_mov_b32_e32 v138, v110
	global_store_dwordx2 v[140:141], v[122:123], off
	v_mov_b64_e32 v[116:117], v[238:239]
	v_mov_b64_e32 v[238:239], v[240:241]
	v_mov_b64_e32 v[240:241], v[242:243]
	v_mov_b64_e32 v[242:243], v[244:245]
	v_mov_b64_e32 v[244:245], v[246:247]
	v_mov_b64_e32 v[246:247], v[248:249]
	v_mov_b64_e32 v[248:249], v[250:251]
	s_cbranch_scc1 .LBB0_275
.LBB0_273:
	s_branch .LBB0_272
.LBB0_275:
	v_lshl_add_u32 v4, s47, 2, v43
	s_mov_b32 s8, 0x30000
	v_mad_u64_u32 v[98:99], s[8:9], v4, s8, v[94:95]
	v_or_b32_e32 v4, s66, v98
	ds_read_b128 v[98:101], v83
	v_lshlrev_b64 v[102:103], 1, v[4:5]
	v_lshl_add_u64 v[104:105], s[16:17], 0, v[102:103]
	v_lshl_add_u64 v[102:103], s[24:25], 0, v[102:103]
	s_waitcnt lgkmcnt(0)
	global_store_dwordx4 v[104:105], v[98:101], off
	ds_read_b128 v[98:101], v85
	s_waitcnt lgkmcnt(0)
	global_store_dwordx4 v[102:103], v[98:101], off
	ds_read_b128 v[98:101], v87
	v_or_b32_e32 v102, 0x200, v4
	v_mov_b32_e32 v103, v5
	v_lshlrev_b64 v[102:103], 1, v[102:103]
	v_lshl_add_u64 v[104:105], s[16:17], 0, v[102:103]
	s_waitcnt lgkmcnt(0)
	global_store_dwordx4 v[104:105], v[98:101], off
	ds_read_b128 v[98:101], v89
	v_lshl_add_u64 v[102:103], s[24:25], 0, v[102:103]
	s_waitcnt lgkmcnt(0)
	global_store_dwordx4 v[102:103], v[98:101], off
	ds_read_b128 v[98:101], v91
	v_or_b32_e32 v102, 0x400, v4
	v_mov_b32_e32 v103, v5
	v_lshlrev_b64 v[102:103], 1, v[102:103]
	v_lshl_add_u64 v[104:105], s[16:17], 0, v[102:103]
	s_waitcnt lgkmcnt(0)
	global_store_dwordx4 v[104:105], v[98:101], off
	ds_read_b128 v[98:101], v93
	v_lshl_add_u64 v[102:103], s[24:25], 0, v[102:103]
	v_or_b32_e32 v4, 0x600, v4
	s_waitcnt lgkmcnt(0)
	global_store_dwordx4 v[102:103], v[98:101], off
	ds_read_b128 v[98:101], v95
	v_lshlrev_b64 v[102:103], 1, v[4:5]
	v_lshl_add_u64 v[104:105], s[16:17], 0, v[102:103]
	v_lshl_add_u64 v[102:103], s[24:25], 0, v[102:103]
	s_waitcnt lgkmcnt(0)
	global_store_dwordx4 v[104:105], v[98:101], off
	ds_read_b128 v[98:101], v111
	s_waitcnt lgkmcnt(0)
	global_store_dwordx4 v[102:103], v[98:101], off

; #define LAS __attribute__((address_space(3)))
; __device__ __forceinline__ unsigned pk2(float lo, float hi) { const bf2_t r = __builtin_convertvector((f32x2){lo, hi}, bf2_t); unsigned u; __builtin_memcpy(&u, &r, 4); return u; }
; __device__ __forceinline__ void rwkv_chunk_item(const P& p, const Ctx& c, int seg, int w, bool save) {
;     ...
;         if (c.wv == 0) {
;             float u[16];
; #pragma unroll
;             for (int p2 = 0; p2 < 8; ++p2) { f32x2 acc = (f32x2){XF[c.lane * 17 + 2 * p2], XF[c.lane * 17 + 2 * p2 + 1]};
; #pragma unroll
;                 for (int s2 = 0; s2 < 2 * p2; ++s2) { const f32x2 m = *(const LAS f32x2*)(MABT + s2 * 20 + 2 * p2); acc += (f32x2){u[s2], u[s2]} * m; }
;                 u[2 * p2] = acc.x;
;                 u[2 * p2 + 1] = acc.y + acc.x * MABT[(2 * p2) * 20 + 2 * p2 + 1]; }
;             *(LAS u32x4*)(UV + c.lane * 40) = (u32x4){pk2(u[0], u[1]), pk2(u[2], u[3]), pk2(u[4], u[5]), pk2(u[6], u[7])};
;             *(LAS u32x4*)(UV + c.lane * 40 + 8) = (u32x4){pk2(u[8], u[9]), pk2(u[10], u[11]), pk2(u[12], u[13]), pk2(u[14], u[15])};
;         }
.LBB0_895:
	v_add_u32_e32 v252, 0xdc00, v81
	v_mov_b32_e32 v253, s88
	ds_read2_b32 v[44:45], v252 offset0:0 offset1:1
	ds_read2_b32 v[48:49], v252 offset0:2 offset1:3
	ds_read2_b32 v[52:53], v252 offset0:4 offset1:5
	ds_read2_b32 v[56:57], v252 offset0:6 offset1:7
	ds_read2_b32 v[60:61], v252 offset0:8 offset1:9
	ds_read2_b32 v[64:65], v252 offset0:10 offset1:11
	ds_read2_b32 v[68:69], v252 offset0:12 offset1:13
	ds_read2_b32 v[72:73], v252 offset0:14 offset1:15
	ds_read_b32 v170, v253 offset:22020
	ds_read_b64 v[156:157], v253 offset:22024
	ds_read_b128 v[230:233], v253 offset:22032
	ds_read_b128 v[124:127], v253 offset:22048
	ds_read_b128 v[176:179], v253 offset:22064
	ds_read_b64 v[158:159], v253 offset:22104
	ds_read_b128 v[234:237], v253 offset:22112
	ds_read_b128 v[128:131], v253 offset:22128
	ds_read_b128 v[180:183], v253 offset:22144
	ds_read_b32 v172, v253 offset:22188
	ds_read_b128 v[238:241], v253 offset:22192
	ds_read_b128 v[132:135], v253 offset:22208
	ds_read_b128 v[184:187], v253 offset:22224
	ds_read_b128 v[242:245], v253 offset:22272
	ds_read_b128 v[136:139], v253 offset:22288
	ds_read_b128 v[188:191], v253 offset:22304
	s_waitcnt lgkmcnt(7)
	v_fma_f32 v46, v170, v44, v45
	v_pk_fma_f32 v[48:49], v[44:45], v[156:157], v[48:49] op_sel_hi:[0,1,1]
	v_pk_fma_f32 v[52:53], v[44:45], v[230:231], v[52:53] op_sel_hi:[0,1,1]
	v_pk_fma_f32 v[56:57], v[44:45], v[232:233], v[56:57] op_sel_hi:[0,1,1]
	v_pk_fma_f32 v[60:61], v[44:45], v[124:125], v[60:61] op_sel_hi:[0,1,1]
	v_pk_fma_f32 v[64:65], v[44:45], v[126:127], v[64:65] op_sel_hi:[0,1,1]
	v_pk_fma_f32 v[68:69], v[44:45], v[176:177], v[68:69] op_sel_hi:[0,1,1]
	v_pk_fma_f32 v[72:73], v[44:45], v[178:179], v[72:73] op_sel_hi:[0,1,1]
	v_pk_fma_f32 v[48:49], v[46:47], v[158:159], v[48:49] op_sel_hi:[0,1,1]
	v_pk_fma_f32 v[52:53], v[46:47], v[234:235], v[52:53] op_sel_hi:[0,1,1]
	v_pk_fma_f32 v[56:57], v[46:47], v[236:237], v[56:57] op_sel_hi:[0,1,1]
	v_pk_fma_f32 v[60:61], v[46:47], v[128:129], v[60:61] op_sel_hi:[0,1,1]
	v_pk_fma_f32 v[64:65], v[46:47], v[130:131], v[64:65] op_sel_hi:[0,1,1]
	v_pk_fma_f32 v[68:69], v[46:47], v[180:181], v[68:69] op_sel_hi:[0,1,1]
	v_pk_fma_f32 v[72:73], v[46:47], v[182:183], v[72:73] op_sel_hi:[0,1,1]
	ds_read_b32 v173, v253 offset:22356
	ds_read_b64 v[160:161], v253 offset:22360
	ds_read_b128 v[140:143], v253 offset:22368
	ds_read_b128 v[192:195], v253 offset:22384
	ds_read_b64 v[162:163], v253 offset:22440
	ds_read_b128 v[144:147], v253 offset:22448
	ds_read_b128 v[196:199], v253 offset:22464
	s_waitcnt lgkmcnt(7)
	v_fma_f32 v50, v172, v48, v49
	v_pk_fma_f32 v[52:53], v[48:49], v[238:239], v[52:53] op_sel_hi:[0,1,1]
	v_pk_fma_f32 v[56:57], v[48:49], v[240:241], v[56:57] op_sel_hi:[0,1,1]
	v_pk_fma_f32 v[60:61], v[48:49], v[132:133], v[60:61] op_sel_hi:[0,1,1]
	v_pk_fma_f32 v[64:65], v[48:49], v[134:135], v[64:65] op_sel_hi:[0,1,1]
	v_pk_fma_f32 v[68:69], v[48:49], v[184:185], v[68:69] op_sel_hi:[0,1,1]
	v_pk_fma_f32 v[72:73], v[48:49], v[186:187], v[72:73] op_sel_hi:[0,1,1]
	v_pk_fma_f32 v[52:53], v[50:51], v[242:243], v[52:53] op_sel_hi:[0,1,1]
	v_pk_fma_f32 v[56:57], v[50:51], v[244:245], v[56:57] op_sel_hi:[0,1,1]
	v_pk_fma_f32 v[60:61], v[50:51], v[136:137], v[60:61] op_sel_hi:[0,1,1]
	v_pk_fma_f32 v[64:65], v[50:51], v[138:139], v[64:65] op_sel_hi:[0,1,1]
	v_pk_fma_f32 v[68:69], v[50:51], v[188:189], v[68:69] op_sel_hi:[0,1,1]
	v_pk_fma_f32 v[72:73], v[50:51], v[190:191], v[72:73] op_sel_hi:[0,1,1]
	ds_read_b32 v174, v253 offset:22524
	ds_read_b128 v[148:151], v253 offset:22528
	ds_read_b128 v[200:203], v253 offset:22544
	ds_read_b128 v[152:155], v253 offset:22608
	ds_read_b128 v[204:207], v253 offset:22624
	s_waitcnt lgkmcnt(5)
; #define LAS __attribute__((address_space(3)))
; __device__ __forceinline__ unsigned pk2(float lo, float hi) { const bf2_t r = __builtin_convertvector((f32x2){lo, hi}, bf2_t); unsigned u; __builtin_memcpy(&u, &r, 4); return u; }
; __device__ __forceinline__ void rwkv_chunk_item(const P& p, const Ctx& c, int seg, int w, bool save) {
;     ...
;         if (c.wv == 0) {
;             float u[16];
; #pragma unroll
;             for (int p2 = 0; p2 < 8; ++p2) { f32x2 acc = (f32x2){XF[c.lane * 17 + 2 * p2], XF[c.lane * 17 + 2 * p2 + 1]};
; #pragma unroll
;                 for (int s2 = 0; s2 < 2 * p2; ++s2) { const f32x2 m = *(const LAS f32x2*)(MABT + s2 * 20 + 2 * p2); acc += (f32x2){u[s2], u[s2]} * m; }
;                 u[2 * p2] = acc.x;
;                 u[2 * p2 + 1] = acc.y + acc.x * MABT[(2 * p2) * 20 + 2 * p2 + 1]; }
;             *(LAS u32x4*)(UV + c.lane * 40) = (u32x4){pk2(u[0], u[1]), pk2(u[2], u[3]), pk2(u[4], u[5]), pk2(u[6], u[7])};
;             *(LAS u32x4*)(UV + c.lane * 40 + 8) = (u32x4){pk2(u[8], u[9]), pk2(u[10], u[11]), pk2(u[12], u[13]), pk2(u[14], u[15])};
;         }
	v_fma_f32 v54, v173, v52, v53
	v_pk_fma_f32 v[56:57], v[52:53], v[160:161], v[56:57] op_sel_hi:[0,1,1]
	v_pk_fma_f32 v[60:61], v[52:53], v[140:141], v[60:61] op_sel_hi:[0,1,1]
	v_pk_fma_f32 v[64:65], v[52:53], v[142:143], v[64:65] op_sel_hi:[0,1,1]
	v_pk_fma_f32 v[68:69], v[52:53], v[192:193], v[68:69] op_sel_hi:[0,1,1]
	v_pk_fma_f32 v[72:73], v[52:53], v[194:195], v[72:73] op_sel_hi:[0,1,1]
	v_pk_fma_f32 v[56:57], v[54:55], v[162:163], v[56:57] op_sel_hi:[0,1,1]
	v_pk_fma_f32 v[60:61], v[54:55], v[144:145], v[60:61] op_sel_hi:[0,1,1]
	v_pk_fma_f32 v[64:65], v[54:55], v[146:147], v[64:65] op_sel_hi:[0,1,1]
	v_pk_fma_f32 v[68:69], v[54:55], v[196:197], v[68:69] op_sel_hi:[0,1,1]
	v_pk_fma_f32 v[72:73], v[54:55], v[198:199], v[72:73] op_sel_hi:[0,1,1]
	ds_read_b32 v248, v253 offset:22692
	ds_read_b64 v[164:165], v253 offset:22696
	ds_read_b128 v[208:211], v253 offset:22704
	ds_read_b64 v[166:167], v253 offset:22776
	ds_read_b128 v[218:221], v253 offset:22784
	s_waitcnt lgkmcnt(5)
	v_fma_f32 v58, v174, v56, v57
	v_pk_fma_f32 v[60:61], v[56:57], v[148:149], v[60:61] op_sel_hi:[0,1,1]
	v_pk_fma_f32 v[64:65], v[56:57], v[150:151], v[64:65] op_sel_hi:[0,1,1]
	v_pk_fma_f32 v[68:69], v[56:57], v[200:201], v[68:69] op_sel_hi:[0,1,1]
	v_pk_fma_f32 v[72:73], v[56:57], v[202:203], v[72:73] op_sel_hi:[0,1,1]
	v_pk_fma_f32 v[60:61], v[58:59], v[152:153], v[60:61] op_sel_hi:[0,1,1]
	v_pk_fma_f32 v[64:65], v[58:59], v[154:155], v[64:65] op_sel_hi:[0,1,1]
	v_pk_fma_f32 v[68:69], v[58:59], v[204:205], v[68:69] op_sel_hi:[0,1,1]
	v_pk_fma_f32 v[72:73], v[58:59], v[206:207], v[72:73] op_sel_hi:[0,1,1]
	ds_read_b32 v249, v253 offset:22860
	ds_read_b128 v[222:225], v253 offset:22864
	ds_read_b128 v[226:229], v253 offset:22944
	s_waitcnt lgkmcnt(3)
	v_fma_f32 v62, v248, v60, v61
	v_pk_fma_f32 v[64:65], v[60:61], v[164:165], v[64:65] op_sel_hi:[0,1,1]
	v_pk_fma_f32 v[68:69], v[60:61], v[208:209], v[68:69] op_sel_hi:[0,1,1]
	v_pk_fma_f32 v[72:73], v[60:61], v[210:211], v[72:73] op_sel_hi:[0,1,1]
	v_pk_fma_f32 v[64:65], v[62:63], v[166:167], v[64:65] op_sel_hi:[0,1,1]
	v_pk_fma_f32 v[68:69], v[62:63], v[218:219], v[68:69] op_sel_hi:[0,1,1]
	v_pk_fma_f32 v[72:73], v[62:63], v[220:221], v[72:73] op_sel_hi:[0,1,1]
	ds_read_b32 v250, v253 offset:23028
	ds_read_b64 v[168:169], v253 offset:23032
	ds_read_b64 v[246:247], v253 offset:23112
	s_waitcnt lgkmcnt(3)
	v_fma_f32 v66, v249, v64, v65
	v_pk_fma_f32 v[68:69], v[64:65], v[222:223], v[68:69] op_sel_hi:[0,1,1]
	v_pk_fma_f32 v[72:73], v[64:65], v[224:225], v[72:73] op_sel_hi:[0,1,1]
	v_pk_fma_f32 v[68:69], v[66:67], v[226:227], v[68:69] op_sel_hi:[0,1,1]
	v_pk_fma_f32 v[72:73], v[66:67], v[228:229], v[72:73] op_sel_hi:[0,1,1]
	ds_read_b32 v251, v253 offset:23196
	s_waitcnt lgkmcnt(1)
	v_fma_f32 v120, v250, v68, v69
	v_pk_fma_f32 v[72:73], v[68:69], v[168:169], v[72:73] op_sel_hi:[0,1,1]
	v_pk_fma_f32 v[72:73], v[120:121], v[246:247], v[72:73] op_sel_hi:[0,1,1]
	s_waitcnt lgkmcnt(0)
	v_fma_f32 v122, v251, v72, v73
	v_add_u32_e32 v252, s88, v80
	v_cvt_pk_bf16_f32 v44, v44, v46
	v_cvt_pk_bf16_f32 v45, v48, v50
	v_cvt_pk_bf16_f32 v46, v52, v54
	v_cvt_pk_bf16_f32 v47, v56, v58
	ds_write_b128 v252, v[44:47] offset:14336
	v_cvt_pk_bf16_f32 v44, v60, v62
	v_cvt_pk_bf16_f32 v45, v64, v66
	v_cvt_pk_bf16_f32 v46, v68, v120
	v_cvt_pk_bf16_f32 v47, v72, v122
	ds_write_b128 v252, v[44:47] offset:14352
